# final in-place RMSNorm row loop: gamma loaded once per item, next row's loads issued before the current row's arithmetic and stores
# speedup vs baseline: 1.0006x; 1.0006x over previous
; __device__ __forceinline__ float wave_sum(float v) { v += swz_xor<1>(v); v += swz_xor<2>(v); v += swz_xor<4>(v); v += swz_xor<8>(v); v += swz_xor<16>(v); return half_sum(v); }
; #define INP(i) ((const float*)tab_get(lds, (i)))
; #define OUTP() ((float*)tab_get(lds, 30))
; #define fresh_lane() (my_tid(lds) & 63)
; #define QNEXT(ctrw, dst) do { __syncthreads(); if (my_tid(lds) == 0) *(volatile LAS int*)(lds + TAB_OFF + 264) = (int)atomicAdd((unsigned*)tab_get(lds, 31) + 8192 + 64 * (ctrw), 1u); \
;         __syncthreads(); dst = __builtin_amdgcn_readfirstlane(*(volatile LAS int*)(lds + TAB_OFF + 264)); } while (0)
; __device__ __forceinline__ void rms_row_f32_inplace(float* xrow, const float* g, int lane) {
;     f32x4* xr = (f32x4*)xrow + lane; f32x4 v[4]; float s = 0.f;
; #pragma unroll
;     for (int j = 0; j < 4; ++j) { v[j] = xr[64 * j]; s += (v[j].x * v[j].x + v[j].y * v[j].y) + (v[j].z * v[j].z + v[j].w * v[j].w); }
;     const float rstd = rsqrtf(wave_sum(s) * (1.f / DM) + EPS);
; #pragma unroll
;     for (int j = 0; j < 4; ++j) { const f32x4 gg = ((const f32x4*)g)[lane + 64 * j]; xr[64 * j] = v[j] * rstd * gg; }
; }
; __global__ void __launch_bounds__(512, 2) mega_fwd(Params p) {
;     ...
;         { const int lane = fresh_lane(); float* X = OUTP(); const float* g = INP(29);
;           for (;;) { int it; QNEXT(4, it); if (it >= MP / 64) break;
; #pragma unroll 1
;               for (int k = 0; k < 8; ++k) rms_row_f32_inplace(X + (size_t)(it * 64 + wave * 8 + k) * DM, g, lane); } }
.LBB0_1717:
	s_or_b64 exec, exec, s[2:3]
	s_waitcnt lgkmcnt(0)
	s_barrier
	ds_read_b32 v4, v7
	s_mov_b64 s[2:3], -1
	s_waitcnt lgkmcnt(0)
	v_readfirstlane_b32 s6, v4
	s_cmpk_gt_i32 s6, 0x1ff
	s_cbranch_scc1 .LBB0_1714
	s_lshr_b32 s2, s6, 5
	s_and_b32 s3, s6, 31
	s_lshl_b32 s6, s2, 1
	s_or_b32 s6, s6, 1
	s_cmp_lt_u32 s2, 8
	s_cselect_b32 s2, 0, 17
	s_sub_i32 s6, s6, s2
	s_lshl_b32 s6, s6, 5
	s_or_b32 s6, s6, s3
	s_lshl_b32 s2, s6, 6
	s_add_i32 s2, s2, s70
	s_ashr_i32 s3, s2, 31
	s_lshl_b64 s[2:3], s[2:3], 12
	v_lshl_add_u64 v[4:5], v[2:3], 0, s[2:3]
	s_mov_b64 s[2:3], 0
	s_mov_b64 s[98:99], 0x1000
	global_load_dwordx4 v[40:43], v[0:1], off
	global_load_dwordx4 v[44:47], v[0:1], off offset:1024
	global_load_dwordx4 v[48:51], v[0:1], off offset:2048
	global_load_dwordx4 v[52:55], v[0:1], off offset:3072
	global_load_dwordx4 v[56:59], v[4:5], off
	global_load_dwordx4 v[60:63], v[4:5], off offset:1024
	global_load_dwordx4 v[64:67], v[4:5], off offset:2048
	global_load_dwordx4 v[68:71], v[4:5], off offset:3072
	s_waitcnt vmcnt(0)
.LBB0_1719:
	v_lshl_add_u64 v[30:31], v[4:5], 0, s[2:3]
	s_add_u32 s2, s2, 0x1000
	s_addc_u32 s3, s3, 0
	s_cmpk_eq_u32 s2, 0x8000
	s_waitcnt vmcnt(4) lgkmcnt(0)
	v_mov_b32_e32 v10, v56
	v_mov_b32_e32 v11, v57
	v_mov_b32_e32 v12, v58
	v_mov_b32_e32 v13, v59
	v_mov_b32_e32 v14, v60
	v_mov_b32_e32 v15, v61
	v_mov_b32_e32 v16, v62
	v_mov_b32_e32 v17, v63
	v_mov_b32_e32 v18, v64
	v_mov_b32_e32 v19, v65
	v_mov_b32_e32 v20, v66
	v_mov_b32_e32 v21, v67
	v_mov_b32_e32 v22, v68
	v_mov_b32_e32 v23, v69
	v_mov_b32_e32 v24, v70
	v_mov_b32_e32 v25, v71
	s_cbranch_scc1 .Lfn_nopf
	v_lshl_add_u64 v[72:73], v[30:31], 0, s[98:99]
	global_load_dwordx4 v[56:59], v[72:73], off
	global_load_dwordx4 v[60:63], v[72:73], off offset:1024
	global_load_dwordx4 v[64:67], v[72:73], off offset:2048
	global_load_dwordx4 v[68:71], v[72:73], off offset:3072
.Lfn_nopf:
	v_mul_f32_e32 v9, v11, v11
	v_mul_f32_e32 v32, v13, v13
	v_mul_f32_e32 v33, v15, v15
	v_mul_f32_e32 v34, v17, v17
	v_mul_f32_e32 v35, v19, v19
	v_mul_f32_e32 v36, v21, v21
	v_fmac_f32_e32 v9, v10, v10
	v_fmac_f32_e32 v32, v12, v12
	v_fmac_f32_e32 v33, v14, v14
	v_fmac_f32_e32 v34, v16, v16
	v_mul_f32_e32 v37, v23, v23
	v_mul_f32_e32 v38, v25, v25
	v_fmac_f32_e32 v35, v18, v18
	v_fmac_f32_e32 v36, v20, v20
	v_add_f32_e32 v9, v9, v32
	v_add_f32_e32 v32, v33, v34
	v_fmac_f32_e32 v37, v22, v22
	v_fmac_f32_e32 v38, v24, v24
	v_add_f32_e32 v33, v35, v36
	v_add_f32_e32 v9, v9, v32
	v_add_f32_e32 v34, v37, v38
	v_add_f32_e32 v9, v9, v33
	v_add_f32_e32 v9, v9, v34
	ds_swizzle_b32 v32, v9 offset:swizzle(SWAP,1)
	s_waitcnt lgkmcnt(0)
	v_add_f32_e32 v9, v9, v32
	ds_swizzle_b32 v32, v9 offset:swizzle(SWAP,2)
	s_waitcnt lgkmcnt(0)
	v_add_f32_e32 v9, v9, v32
	ds_swizzle_b32 v32, v9 offset:swizzle(SWAP,4)
	s_waitcnt lgkmcnt(0)
	v_add_f32_e32 v9, v9, v32
	ds_swizzle_b32 v32, v9 offset:swizzle(SWAP,8)
	s_waitcnt lgkmcnt(0)
	v_add_f32_e32 v9, v9, v32
	ds_swizzle_b32 v32, v9 offset:swizzle(SWAP,16)
	s_waitcnt lgkmcnt(0)
	v_add_f32_e32 v9, v9, v32
	v_mov_b32_e32 v32, v9
	s_nop 1
	v_permlane32_swap_b32_e32 v9, v32
	v_add_f32_e32 v9, v9, v32
	v_fmamk_f32 v9, v9, 0x3a800000, v8
	v_mul_f32_e32 v32, 0x4b800000, v9
	v_cmp_gt_f32_e32 vcc, s5, v9
	s_nop 1
	v_cndmask_b32_e32 v9, v9, v32, vcc
	v_rsq_f32_e32 v9, v9
	s_nop 0
	v_mul_f32_e32 v32, 0x45800000, v9
	v_cndmask_b32_e32 v32, v9, v32, vcc
	v_pk_mul_f32 v[10:11], v[10:11], v[32:33] op_sel_hi:[1,0]
	v_pk_mul_f32 v[12:13], v[12:13], v[32:33] op_sel_hi:[1,0]
	v_pk_mul_f32 v[14:15], v[14:15], v[32:33] op_sel_hi:[1,0]
	v_pk_mul_f32 v[16:17], v[16:17], v[32:33] op_sel_hi:[1,0]
	v_pk_mul_f32 v[10:11], v[40:41], v[10:11]
	v_pk_mul_f32 v[12:13], v[42:43], v[12:13]
	global_store_dwordx4 v[30:31], v[10:13], off
	v_pk_mul_f32 v[14:15], v[44:45], v[14:15]
	v_pk_mul_f32 v[16:17], v[46:47], v[16:17]
	v_pk_mul_f32 v[18:19], v[18:19], v[32:33] op_sel_hi:[1,0]
	v_pk_mul_f32 v[20:21], v[20:21], v[32:33] op_sel_hi:[1,0]
	global_store_dwordx4 v[30:31], v[14:17], off offset:1024
	v_pk_mul_f32 v[18:19], v[48:49], v[18:19]
	v_pk_mul_f32 v[20:21], v[50:51], v[20:21]
	v_pk_mul_f32 v[22:23], v[22:23], v[32:33] op_sel_hi:[1,0]
	v_pk_mul_f32 v[24:25], v[24:25], v[32:33] op_sel_hi:[1,0]
	global_store_dwordx4 v[30:31], v[18:21], off offset:2048
	v_pk_mul_f32 v[22:23], v[52:53], v[22:23]
	v_pk_mul_f32 v[24:25], v[54:55], v[24:25]
	global_store_dwordx4 v[30:31], v[22:25], off offset:3072
	s_cbranch_scc0 .LBB0_1719
	s_mov_b64 s[2:3], 0
	s_branch .LBB0_1714
